# P7 residual epilogue: 16 tile loads in one burst before the drain wait
# baseline (speedup 1.0000x reference)
; __device__ __forceinline__ unsigned cvt_pk_bf16(float lo, float hi) { cvf32x2_t v = {lo, hi}; cvbf16x2_t b = __builtin_convertvector(v, cvbf16x2_t); return __builtin_bit_cast(unsigned, b); }
; #define PG8_WAIT_V(n) asm volatile("s_waitcnt vmcnt(" #n ")" ::: "memory")
; #define PG8_BAR __builtin_amdgcn_s_barrier()
; __device__ __forceinline__ float bfl(unsigned w) { return __uint_as_float(w << 16); }
; __device__ __forceinline__ float bfh(unsigned w) { return __uint_as_float(w & 0xffff0000u); }
; template <class Epi, class Sched, bool ALIGN_EPI = false, bool SP2 = false>
; __device__ __forceinline__ void gemm_phase(PG8_LAS unsigned char* lds, const Gemm g, const Sched& S, const Epi& E) {
;     ...
;     PG8_WAIT_V(0);
;     if constexpr (!ALIGN_EPI) { if (wr == 0) PG8_BAR; }
;     PG8_BAR;
;     if constexpr (Epi::AFTER_DRAIN) { E.fused(acc, cur, wr, wc, fr, fq, lds, wid, lane); S.done(cur); }
;     __device__ __forceinline__ void fused(f32x4 (&acc)[2][2][4][2], const Unit& u, int wr, int wc, int fr, int fq, PG8_LAS unsigned char* lds, int wid, int lane) const {
;     ...
;             for (int m = 0; m < 4; ++m) { const int row = row0 + ai * HALF + m * 16; const size_t off = (size_t)row * 1024 + col0; float ss = 0.f;
; #pragma unroll
;                 for (int bj = 0; bj < 2; ++bj) { const size_t o = off + bj * HALF; f32x4 x0, x1;
;                     if (xin32) { x0 = *(const f32x4*)(xin32 + o); x1 = *(const f32x4*)(xin32 + o + 4); }
;                     else { const u32x4 w = *(const u32x4*)(xb + o); x0 = (f32x4){bfl(w.x), bfh(w.x), bfl(w.y), bfh(w.y)}; x1 = (f32x4){bfl(w.z), bfh(w.z), bfl(w.w), bfh(w.w)}; }
;                     const f32x4 v0 = x0 + acc[ai][bj][m][0] * scale, v1 = x1 + acc[ai][bj][m][1] * scale;
;                     ss += ((v0[0] * v0[0] + v0[1] * v0[1]) + (v0[2] * v0[2] + v0[3] * v0[3])) + ((v1[0] * v1[0] + v1[1] * v1[1]) + (v1[2] * v1[2] + v1[3] * v1[3]));
;                     u32x4 w; w.x = cvt_pk_bf16(v0[0], v0[1]); w.y = cvt_pk_bf16(v0[2], v0[3]); w.z = cvt_pk_bf16(v1[0], v1[1]); w.w = cvt_pk_bf16(v1[2], v1[3]); st_wt16(xb + o, w); }
;                 ss += __shfl_xor(ss, 16); ss += __shfl_xor(ss, 32);
;                 if (fq == 0) P[(ai * HALF + wr * 64 + m * 16 + fr) * 4 + wc] = ss; }
.LBB0_1014:
	s_lshl_b32 s6, s10, 8
	s_add_i32 s5, s6, s43
	s_lshl_b32 s4, s11, 5
	v_or_b32_e32 v128, s5, v150
	s_lshl_b32 s5, s61, 8
	s_or_b32 s4, s5, s4
	v_and_or_b32 v130, v149, 24, s4
	v_ashrrev_i32_e32 v129, 31, v128
	v_ashrrev_i32_e32 v131, 31, v130
	v_lshlrev_b64 v[132:133], 10, v[128:129]
	v_lshl_add_u64 v[132:133], v[132:133], 0, v[130:131]
	v_lshl_add_u64 v[142:143], v[132:133], 1, s[54:55]
	s_mov_b64 s[96:97], 0x8000
	v_lshl_add_u64 v[154:155], v[142:143], 0, s[96:97]
	s_mov_b64 s[96:97], 0x10000
	v_lshl_add_u64 v[210:211], v[142:143], 0, s[96:97]
	s_mov_b64 s[96:97], 0x18000
	v_lshl_add_u64 v[224:225], v[142:143], 0, s[96:97]
	s_mov_b64 s[96:97], 0x40000
	v_lshl_add_u64 v[226:227], v[142:143], 0, s[96:97]
	s_mov_b64 s[96:97], 0x48000
	v_lshl_add_u64 v[228:229], v[142:143], 0, s[96:97]
	s_mov_b64 s[96:97], 0x50000
	v_lshl_add_u64 v[230:231], v[142:143], 0, s[96:97]
	s_mov_b64 s[96:97], 0x58000
	v_lshl_add_u64 v[232:233], v[142:143], 0, s[96:97]
	global_load_dwordx4 v[156:159], v[142:143], off
	global_load_dwordx4 v[160:163], v[142:143], off offset:256
	global_load_dwordx4 v[164:167], v[154:155], off
	global_load_dwordx4 v[168:171], v[154:155], off offset:256
	global_load_dwordx4 v[172:175], v[210:211], off
	global_load_dwordx4 v[176:179], v[210:211], off offset:256
	global_load_dwordx4 v[180:183], v[224:225], off
	global_load_dwordx4 v[184:187], v[224:225], off offset:256
	global_load_dwordx4 v[188:191], v[226:227], off
	global_load_dwordx4 v[192:195], v[226:227], off offset:256
	global_load_dwordx4 v[196:199], v[228:229], off
	global_load_dwordx4 v[200:203], v[228:229], off offset:256
	global_load_dwordx4 v[204:207], v[230:231], off
	global_load_dwordx4 v[212:215], v[230:231], off offset:256
	global_load_dwordx4 v[216:219], v[232:233], off
	global_load_dwordx4 v[220:223], v[232:233], off offset:256
	s_waitcnt vmcnt(0)
	s_cmpk_gt_u32 s30, 0xff
	s_cbranch_scc1 .LBB0_1016
	s_barrier
.LBB0_1016:
	s_barrier
	v_mbcnt_lo_u32_b32 v132, -1, 0
	v_mbcnt_hi_u32_b32 v132, -1, v132
	v_and_b32_e32 v144, 64, v132
	v_xor_b32_e32 v133, 16, v132
	v_add_u32_e32 v144, 64, v144
	v_xor_b32_e32 v145, 32, v132
	v_cmp_lt_i32_e32 vcc, v133, v144
	s_lshl_b32 s7, s11, 2
	s_add_i32 s7, s7, 0
	v_cndmask_b32_e32 v133, v132, v133, vcc
	v_cmp_lt_i32_e32 vcc, v145, v144
	v_lshlrev_b32_e32 v133, 2, v133
	v_cmp_gt_u32_e64 s[4:5], 16, v208
	v_cndmask_b32_e32 v132, v132, v145, vcc
	v_lshlrev_b32_e32 v132, 2, v132
	v_lshlrev_b32_e32 v144, 16, v156
	v_and_b32_e32 v145, 0xffff0000, v156
	v_lshlrev_b32_e32 v134, 16, v157
	v_and_b32_e32 v135, 0xffff0000, v157
	v_lshlrev_b32_e32 v146, 16, v158
	v_and_b32_e32 v147, 0xffff0000, v158
	v_lshlrev_b32_e32 v136, 16, v159
	v_and_b32_e32 v137, 0xffff0000, v159
	v_lshlrev_b32_e32 v150, 16, v160
	v_and_b32_e32 v151, 0xffff0000, v160
	v_lshlrev_b32_e32 v138, 16, v161
	v_and_b32_e32 v139, 0xffff0000, v161
	v_lshlrev_b32_e32 v152, 16, v162
	v_and_b32_e32 v153, 0xffff0000, v162
	v_lshlrev_b32_e32 v140, 16, v163
	v_and_b32_e32 v141, 0xffff0000, v163
	v_pk_add_f32 v[126:127], v[126:127], v[134:135]
	v_pk_add_f32 v[124:125], v[124:125], v[144:145]
	v_pk_add_f32 v[122:123], v[122:123], v[136:137]
	v_pk_add_f32 v[120:121], v[120:121], v[146:147]
	v_pk_add_f32 v[118:119], v[118:119], v[138:139]
	v_pk_add_f32 v[116:117], v[116:117], v[150:151]
	v_pk_add_f32 v[134:135], v[114:115], v[140:141]
	v_pk_add_f32 v[136:137], v[112:113], v[152:153]
	v_mul_f32_e32 v115, v125, v125
	v_mul_f32_e32 v138, v127, v127
	v_mul_f32_e32 v139, v121, v121
	v_mul_f32_e32 v140, v123, v123
	v_cvt_pk_bf16_f32 v112, v124, v125
	v_cvt_pk_bf16_f32 v113, v126, v127
	v_cvt_pk_bf16_f32 v114, v120, v121
	v_mul_f32_e32 v121, v117, v117
	v_mul_f32_e32 v125, v119, v119
	v_mul_f32_e32 v127, v137, v137
	v_mul_f32_e32 v141, v135, v135
	v_fmac_f32_e32 v115, v124, v124
	v_fmac_f32_e32 v138, v126, v126
	v_fmac_f32_e32 v139, v120, v120
	v_fmac_f32_e32 v140, v122, v122
	v_fmac_f32_e32 v121, v116, v116
	v_fmac_f32_e32 v125, v118, v118
	v_fmac_f32_e32 v127, v136, v136
	v_fmac_f32_e32 v141, v134, v134
	v_add_f32_e32 v115, v115, v138
	v_add_f32_e32 v120, v139, v140
	v_add_f32_e32 v121, v121, v125
	v_add_f32_e32 v124, v127, v141
	v_add_f32_e32 v115, v115, v120
	v_add_f32_e32 v120, v121, v124
	v_add_f32_e32 v120, v115, v120
	ds_bpermute_b32 v121, v133, v120
	v_cvt_pk_bf16_f32 v115, v122, v123
	global_store_dwordx4 v[142:143], v[112:115], off
	v_cvt_pk_bf16_f32 v116, v116, v117
	v_cvt_pk_bf16_f32 v117, v118, v119
	s_waitcnt lgkmcnt(0)
	v_add_f32_e32 v113, v120, v121
	ds_bpermute_b32 v114, v132, v113
	v_cvt_pk_bf16_f32 v118, v136, v137
	v_cvt_pk_bf16_f32 v119, v134, v135
	v_lshl_add_u32 v112, v148, 4, s7
	global_store_dwordx4 v[142:143], v[116:119], off offset:256
	s_and_saveexec_b64 s[10:11], s[4:5]
	s_cbranch_execz .LBB0_1018
	s_waitcnt lgkmcnt(0)
	v_add_f32_e32 v113, v113, v114
	ds_write_b32 v112, v113
; __device__ __forceinline__ unsigned cvt_pk_bf16(float lo, float hi) { cvf32x2_t v = {lo, hi}; cvbf16x2_t b = __builtin_convertvector(v, cvbf16x2_t); return __builtin_bit_cast(unsigned, b); }
; __device__ __forceinline__ float bfl(unsigned w) { return __uint_as_float(w << 16); }
; __device__ __forceinline__ float bfh(unsigned w) { return __uint_as_float(w & 0xffff0000u); }
;     __device__ __forceinline__ void fused(f32x4 (&acc)[2][2][4][2], const Unit& u, int wr, int wc, int fr, int fq, PG8_LAS unsigned char* lds, int wid, int lane) const {
;     ...
;             for (int m = 0; m < 4; ++m) { const int row = row0 + ai * HALF + m * 16; const size_t off = (size_t)row * 1024 + col0; float ss = 0.f;
; #pragma unroll
;                 for (int bj = 0; bj < 2; ++bj) { const size_t o = off + bj * HALF; f32x4 x0, x1;
;                     if (xin32) { x0 = *(const f32x4*)(xin32 + o); x1 = *(const f32x4*)(xin32 + o + 4); }
;                     else { const u32x4 w = *(const u32x4*)(xb + o); x0 = (f32x4){bfl(w.x), bfh(w.x), bfl(w.y), bfh(w.y)}; x1 = (f32x4){bfl(w.z), bfh(w.z), bfl(w.w), bfh(w.w)}; }
;                     const f32x4 v0 = x0 + acc[ai][bj][m][0] * scale, v1 = x1 + acc[ai][bj][m][1] * scale;
;                     ss += ((v0[0] * v0[0] + v0[1] * v0[1]) + (v0[2] * v0[2] + v0[3] * v0[3])) + ((v1[0] * v1[0] + v1[1] * v1[1]) + (v1[2] * v1[2] + v1[3] * v1[3]));
;                     u32x4 w; w.x = cvt_pk_bf16(v0[0], v0[1]); w.y = cvt_pk_bf16(v0[2], v0[3]); w.z = cvt_pk_bf16(v1[0], v1[1]); w.w = cvt_pk_bf16(v1[2], v1[3]); st_wt16(xb + o, w); }
;                 ss += __shfl_xor(ss, 16); ss += __shfl_xor(ss, 32);
;                 if (fq == 0) P[(ai * HALF + wr * 64 + m * 16 + fr) * 4 + wc] = ss; }
.LBB0_1018:
	s_or_b64 exec, exec, s[10:11]
	s_waitcnt lgkmcnt(0)
	v_or_b32_e32 v114, 16, v128
	v_ashrrev_i32_e32 v115, 31, v114
	v_lshlrev_b64 v[114:115], 10, v[114:115]
	v_lshl_add_u64 v[114:115], v[114:115], 0, v[130:131]
	v_lshl_add_u64 v[122:123], v[114:115], 1, s[54:55]
	v_lshlrev_b32_e32 v124, 16, v164
	v_and_b32_e32 v125, 0xffff0000, v164
	v_lshlrev_b32_e32 v114, 16, v165
	v_and_b32_e32 v115, 0xffff0000, v165
	v_lshlrev_b32_e32 v126, 16, v166
	v_and_b32_e32 v127, 0xffff0000, v166
	v_lshlrev_b32_e32 v116, 16, v167
	v_and_b32_e32 v117, 0xffff0000, v167
	v_lshlrev_b32_e32 v134, 16, v168
	v_and_b32_e32 v135, 0xffff0000, v168
	v_lshlrev_b32_e32 v118, 16, v169
	v_and_b32_e32 v119, 0xffff0000, v169
	v_lshlrev_b32_e32 v136, 16, v170
	v_and_b32_e32 v137, 0xffff0000, v170
	v_lshlrev_b32_e32 v120, 16, v171
	v_and_b32_e32 v121, 0xffff0000, v171
	v_pk_add_f32 v[110:111], v[110:111], v[114:115]
	v_pk_add_f32 v[108:109], v[108:109], v[124:125]
	v_pk_add_f32 v[106:107], v[106:107], v[116:117]
	v_pk_add_f32 v[104:105], v[104:105], v[126:127]
	v_pk_add_f32 v[102:103], v[102:103], v[118:119]
	v_pk_add_f32 v[100:101], v[100:101], v[134:135]
	v_pk_add_f32 v[114:115], v[98:99], v[120:121]
	v_pk_add_f32 v[116:117], v[96:97], v[136:137]
	v_mul_f32_e32 v98, v109, v109
	v_mul_f32_e32 v99, v111, v111
	v_mul_f32_e32 v113, v105, v105
	v_mul_f32_e32 v118, v107, v107
	v_cvt_pk_bf16_f32 v96, v108, v109
	v_cvt_pk_bf16_f32 v97, v110, v111
	v_mul_f32_e32 v109, v101, v101
	v_mul_f32_e32 v111, v103, v103
	v_mul_f32_e32 v119, v117, v117
	v_mul_f32_e32 v120, v115, v115
	v_fmac_f32_e32 v98, v108, v108
	v_fmac_f32_e32 v99, v110, v110
	v_fmac_f32_e32 v113, v104, v104
	v_fmac_f32_e32 v118, v106, v106
	v_fmac_f32_e32 v109, v100, v100
	v_fmac_f32_e32 v111, v102, v102
	v_fmac_f32_e32 v119, v116, v116
	v_fmac_f32_e32 v120, v114, v114
	v_add_f32_e32 v98, v98, v99
	v_add_f32_e32 v99, v113, v118
	v_add_f32_e32 v108, v109, v111
	v_add_f32_e32 v109, v119, v120
	v_add_f32_e32 v98, v98, v99
	v_add_f32_e32 v99, v108, v109
	v_add_f32_e32 v108, v98, v99
	ds_bpermute_b32 v109, v133, v108
	v_cvt_pk_bf16_f32 v98, v104, v105
	v_cvt_pk_bf16_f32 v99, v106, v107
	global_store_dwordx4 v[122:123], v[96:99], off
	s_waitcnt lgkmcnt(0)
	s_nop 0
	v_add_f32_e32 v96, v108, v109
	ds_bpermute_b32 v97, v132, v96
	v_cvt_pk_bf16_f32 v98, v100, v101
	v_cvt_pk_bf16_f32 v99, v102, v103
	v_cvt_pk_bf16_f32 v100, v116, v117
	v_cvt_pk_bf16_f32 v101, v114, v115
	global_store_dwordx4 v[122:123], v[98:101], off offset:256
	s_and_saveexec_b64 s[10:11], s[4:5]
	s_cbranch_execz .LBB0_1020
	s_waitcnt lgkmcnt(0)
	v_add_f32_e32 v96, v96, v97
	ds_write_b32 v112, v96 offset:256
.LBB0_1020:
	s_or_b64 exec, exec, s[10:11]
	v_or_b32_e32 v96, 32, v128
	s_waitcnt lgkmcnt(0)
	v_ashrrev_i32_e32 v97, 31, v96
	v_lshlrev_b64 v[96:97], 10, v[96:97]
	v_lshl_add_u64 v[96:97], v[96:97], 0, v[130:131]
	v_lshl_add_u64 v[104:105], v[96:97], 1, s[54:55]
	v_lshlrev_b32_e32 v106, 16, v172
	v_and_b32_e32 v107, 0xffff0000, v172
	v_lshlrev_b32_e32 v96, 16, v173
	v_and_b32_e32 v97, 0xffff0000, v173
	v_lshlrev_b32_e32 v108, 16, v174
	v_and_b32_e32 v109, 0xffff0000, v174
	v_lshlrev_b32_e32 v98, 16, v175
	v_and_b32_e32 v99, 0xffff0000, v175
	v_lshlrev_b32_e32 v110, 16, v176
	v_and_b32_e32 v111, 0xffff0000, v176
	v_lshlrev_b32_e32 v100, 16, v177
	v_and_b32_e32 v101, 0xffff0000, v177
	v_lshlrev_b32_e32 v114, 16, v178
	v_and_b32_e32 v115, 0xffff0000, v178
	v_lshlrev_b32_e32 v102, 16, v179
	v_and_b32_e32 v103, 0xffff0000, v179
	v_pk_add_f32 v[94:95], v[94:95], v[96:97]
	v_pk_add_f32 v[92:93], v[92:93], v[106:107]
	v_pk_add_f32 v[90:91], v[90:91], v[98:99]
	v_pk_add_f32 v[88:89], v[88:89], v[108:109]
	v_pk_add_f32 v[86:87], v[86:87], v[100:101]
	v_pk_add_f32 v[84:85], v[84:85], v[110:111]
	v_pk_add_f32 v[96:97], v[82:83], v[102:103]
	v_pk_add_f32 v[98:99], v[80:81], v[114:115]
	v_mul_f32_e32 v82, v93, v93
	v_mul_f32_e32 v83, v95, v95
	v_mul_f32_e32 v100, v89, v89
	v_mul_f32_e32 v101, v91, v91
	v_cvt_pk_bf16_f32 v80, v92, v93
	v_cvt_pk_bf16_f32 v81, v94, v95
	v_mul_f32_e32 v93, v85, v85
	v_mul_f32_e32 v95, v87, v87
	v_mul_f32_e32 v102, v99, v99
	v_mul_f32_e32 v103, v97, v97
	v_fmac_f32_e32 v82, v92, v92
	v_fmac_f32_e32 v83, v94, v94
	v_fmac_f32_e32 v100, v88, v88
	v_fmac_f32_e32 v101, v90, v90
	v_fmac_f32_e32 v93, v84, v84
	v_fmac_f32_e32 v95, v86, v86
	v_fmac_f32_e32 v102, v98, v98
	v_fmac_f32_e32 v103, v96, v96
	v_add_f32_e32 v82, v82, v83
	v_add_f32_e32 v83, v100, v101
	v_add_f32_e32 v92, v93, v95
	v_add_f32_e32 v93, v102, v103
	v_add_f32_e32 v82, v82, v83
	v_add_f32_e32 v83, v92, v93
	v_add_f32_e32 v92, v82, v83
	ds_bpermute_b32 v93, v133, v92
	v_cvt_pk_bf16_f32 v82, v88, v89
	v_cvt_pk_bf16_f32 v83, v90, v91
	global_store_dwordx4 v[104:105], v[80:83], off
	s_waitcnt lgkmcnt(0)
	s_nop 0
	v_add_f32_e32 v80, v92, v93
	ds_bpermute_b32 v81, v132, v80
	v_cvt_pk_bf16_f32 v82, v84, v85
	v_cvt_pk_bf16_f32 v83, v86, v87
	v_cvt_pk_bf16_f32 v84, v98, v99
	v_cvt_pk_bf16_f32 v85, v96, v97
	global_store_dwordx4 v[104:105], v[82:85], off offset:256
	s_and_saveexec_b64 s[10:11], s[4:5]
	s_cbranch_execz .LBB0_1022
	s_waitcnt lgkmcnt(0)
	v_add_f32_e32 v80, v80, v81
	ds_write_b32 v112, v80 offset:512
; __device__ __forceinline__ unsigned cvt_pk_bf16(float lo, float hi) { cvf32x2_t v = {lo, hi}; cvbf16x2_t b = __builtin_convertvector(v, cvbf16x2_t); return __builtin_bit_cast(unsigned, b); }
; __device__ __forceinline__ float bfl(unsigned w) { return __uint_as_float(w << 16); }
; __device__ __forceinline__ float bfh(unsigned w) { return __uint_as_float(w & 0xffff0000u); }
;     __device__ __forceinline__ void fused(f32x4 (&acc)[2][2][4][2], const Unit& u, int wr, int wc, int fr, int fq, PG8_LAS unsigned char* lds, int wid, int lane) const {
;     ...
;             for (int m = 0; m < 4; ++m) { const int row = row0 + ai * HALF + m * 16; const size_t off = (size_t)row * 1024 + col0; float ss = 0.f;
; #pragma unroll
;                 for (int bj = 0; bj < 2; ++bj) { const size_t o = off + bj * HALF; f32x4 x0, x1;
;                     if (xin32) { x0 = *(const f32x4*)(xin32 + o); x1 = *(const f32x4*)(xin32 + o + 4); }
;                     else { const u32x4 w = *(const u32x4*)(xb + o); x0 = (f32x4){bfl(w.x), bfh(w.x), bfl(w.y), bfh(w.y)}; x1 = (f32x4){bfl(w.z), bfh(w.z), bfl(w.w), bfh(w.w)}; }
;                     const f32x4 v0 = x0 + acc[ai][bj][m][0] * scale, v1 = x1 + acc[ai][bj][m][1] * scale;
;                     ss += ((v0[0] * v0[0] + v0[1] * v0[1]) + (v0[2] * v0[2] + v0[3] * v0[3])) + ((v1[0] * v1[0] + v1[1] * v1[1]) + (v1[2] * v1[2] + v1[3] * v1[3]));
;                     u32x4 w; w.x = cvt_pk_bf16(v0[0], v0[1]); w.y = cvt_pk_bf16(v0[2], v0[3]); w.z = cvt_pk_bf16(v1[0], v1[1]); w.w = cvt_pk_bf16(v1[2], v1[3]); st_wt16(xb + o, w); }
;                 ss += __shfl_xor(ss, 16); ss += __shfl_xor(ss, 32);
;                 if (fq == 0) P[(ai * HALF + wr * 64 + m * 16 + fr) * 4 + wc] = ss; }
.LBB0_1022:
	s_or_b64 exec, exec, s[10:11]
	v_or_b32_e32 v80, 48, v128
	s_waitcnt lgkmcnt(0)
	v_ashrrev_i32_e32 v81, 31, v80
	v_lshlrev_b64 v[80:81], 10, v[80:81]
	v_lshl_add_u64 v[80:81], v[80:81], 0, v[130:131]
	v_lshl_add_u64 v[88:89], v[80:81], 1, s[54:55]
	v_lshlrev_b32_e32 v90, 16, v180
	v_and_b32_e32 v91, 0xffff0000, v180
	v_lshlrev_b32_e32 v80, 16, v181
	v_and_b32_e32 v81, 0xffff0000, v181
	v_lshlrev_b32_e32 v92, 16, v182
	v_and_b32_e32 v93, 0xffff0000, v182
	v_lshlrev_b32_e32 v82, 16, v183
	v_and_b32_e32 v83, 0xffff0000, v183
	v_lshlrev_b32_e32 v94, 16, v184
	v_and_b32_e32 v95, 0xffff0000, v184
	v_lshlrev_b32_e32 v84, 16, v185
	v_and_b32_e32 v85, 0xffff0000, v185
	v_lshlrev_b32_e32 v96, 16, v186
	v_and_b32_e32 v97, 0xffff0000, v186
	v_lshlrev_b32_e32 v86, 16, v187
	v_and_b32_e32 v87, 0xffff0000, v187
	v_pk_add_f32 v[78:79], v[78:79], v[80:81]
	v_pk_add_f32 v[76:77], v[76:77], v[90:91]
	v_pk_add_f32 v[74:75], v[74:75], v[82:83]
	v_pk_add_f32 v[72:73], v[72:73], v[92:93]
	v_pk_add_f32 v[70:71], v[70:71], v[84:85]
	v_pk_add_f32 v[68:69], v[68:69], v[94:95]
	v_pk_add_f32 v[80:81], v[66:67], v[86:87]
	v_pk_add_f32 v[82:83], v[64:65], v[96:97]
	v_mul_f32_e32 v66, v77, v77
	v_mul_f32_e32 v67, v79, v79
	v_mul_f32_e32 v84, v73, v73
	v_mul_f32_e32 v85, v75, v75
	v_cvt_pk_bf16_f32 v64, v76, v77
	v_cvt_pk_bf16_f32 v65, v78, v79
	v_mul_f32_e32 v77, v69, v69
	v_mul_f32_e32 v79, v71, v71
	v_mul_f32_e32 v86, v83, v83
	v_mul_f32_e32 v87, v81, v81
	v_fmac_f32_e32 v66, v76, v76
	v_fmac_f32_e32 v67, v78, v78
	v_fmac_f32_e32 v84, v72, v72
	v_fmac_f32_e32 v85, v74, v74
	v_fmac_f32_e32 v77, v68, v68
	v_fmac_f32_e32 v79, v70, v70
	v_fmac_f32_e32 v86, v82, v82
	v_fmac_f32_e32 v87, v80, v80
	v_add_f32_e32 v66, v66, v67
	v_add_f32_e32 v67, v84, v85
	v_add_f32_e32 v76, v77, v79
	v_add_f32_e32 v77, v86, v87
	v_add_f32_e32 v66, v66, v67
	v_add_f32_e32 v67, v76, v77
	v_add_f32_e32 v76, v66, v67
	ds_bpermute_b32 v77, v133, v76
	v_cvt_pk_bf16_f32 v66, v72, v73
	v_cvt_pk_bf16_f32 v67, v74, v75
	global_store_dwordx4 v[88:89], v[64:67], off
	s_waitcnt lgkmcnt(0)
	s_nop 0
	v_add_f32_e32 v64, v76, v77
	ds_bpermute_b32 v65, v132, v64
	v_cvt_pk_bf16_f32 v66, v68, v69
	v_cvt_pk_bf16_f32 v67, v70, v71
	v_cvt_pk_bf16_f32 v68, v82, v83
	v_cvt_pk_bf16_f32 v69, v80, v81
	global_store_dwordx4 v[88:89], v[66:69], off offset:256
	s_and_saveexec_b64 s[10:11], s[4:5]
	s_cbranch_execz .LBB0_1024
	s_waitcnt lgkmcnt(0)
	v_add_f32_e32 v64, v64, v65
	ds_write_b32 v112, v64 offset:768
.LBB0_1024:
	s_or_b64 exec, exec, s[10:11]
	s_waitcnt lgkmcnt(0)
	v_lshlrev_b64 v[64:65], 10, v[128:129]
	v_lshl_add_u64 v[64:65], v[64:65], 0, v[130:131]
	v_lshl_add_u64 v[64:65], v[64:65], 1, s[54:55]
	v_add_co_u32_e32 v74, vcc, 0x40000, v64
	s_mov_b64 s[10:11], 0x40000
	s_nop 0
	v_addc_co_u32_e32 v75, vcc, 0, v65, vcc
	v_lshl_add_u64 v[76:77], v[64:65], 0, s[10:11]
	v_lshlrev_b32_e32 v78, 16, v188
	v_and_b32_e32 v79, 0xffff0000, v188
	v_lshlrev_b32_e32 v66, 16, v189
	v_and_b32_e32 v67, 0xffff0000, v189
	v_lshlrev_b32_e32 v80, 16, v190
	v_and_b32_e32 v81, 0xffff0000, v190
	v_lshlrev_b32_e32 v68, 16, v191
	v_and_b32_e32 v69, 0xffff0000, v191
	v_lshlrev_b32_e32 v82, 16, v192
	v_and_b32_e32 v83, 0xffff0000, v192
	v_lshlrev_b32_e32 v70, 16, v193
	v_and_b32_e32 v71, 0xffff0000, v193
	v_lshlrev_b32_e32 v84, 16, v194
	v_and_b32_e32 v85, 0xffff0000, v194
	v_lshlrev_b32_e32 v72, 16, v195
	v_and_b32_e32 v73, 0xffff0000, v195
	v_pk_add_f32 v[62:63], v[62:63], v[66:67]
	v_pk_add_f32 v[60:61], v[60:61], v[78:79]
	v_pk_add_f32 v[58:59], v[58:59], v[68:69]
	v_pk_add_f32 v[56:57], v[56:57], v[80:81]
	v_pk_add_f32 v[54:55], v[54:55], v[70:71]
	v_pk_add_f32 v[52:53], v[52:53], v[82:83]
	v_pk_add_f32 v[66:67], v[50:51], v[72:73]
	v_pk_add_f32 v[68:69], v[48:49], v[84:85]
	v_mul_f32_e32 v50, v61, v61
	v_mul_f32_e32 v51, v63, v63
	v_mul_f32_e32 v70, v57, v57
	v_mul_f32_e32 v71, v59, v59
	v_cvt_pk_bf16_f32 v48, v60, v61
	v_cvt_pk_bf16_f32 v49, v62, v63
	v_mul_f32_e32 v61, v53, v53
	v_mul_f32_e32 v63, v55, v55
	v_mul_f32_e32 v72, v69, v69
	v_mul_f32_e32 v73, v67, v67
	v_fmac_f32_e32 v50, v60, v60
	v_fmac_f32_e32 v51, v62, v62
	v_fmac_f32_e32 v70, v56, v56
	v_fmac_f32_e32 v71, v58, v58
	v_fmac_f32_e32 v61, v52, v52
	v_fmac_f32_e32 v63, v54, v54
	v_fmac_f32_e32 v72, v68, v68
	v_fmac_f32_e32 v73, v66, v66
	v_add_f32_e32 v50, v50, v51
	v_add_f32_e32 v51, v70, v71
	v_add_f32_e32 v60, v61, v63
	v_add_f32_e32 v61, v72, v73
	v_add_f32_e32 v50, v50, v51
	v_add_f32_e32 v51, v60, v61
	v_add_f32_e32 v60, v50, v51
	ds_bpermute_b32 v61, v133, v60
	v_cvt_pk_bf16_f32 v50, v56, v57
	v_cvt_pk_bf16_f32 v51, v58, v59
	global_store_dwordx4 v[74:75], v[48:51], off
	s_waitcnt lgkmcnt(0)
	s_nop 0
	v_add_f32_e32 v48, v60, v61
	ds_bpermute_b32 v49, v132, v48
	v_cvt_pk_bf16_f32 v50, v52, v53
	v_cvt_pk_bf16_f32 v51, v54, v55
	v_cvt_pk_bf16_f32 v52, v68, v69
	v_cvt_pk_bf16_f32 v53, v66, v67
	global_store_dwordx4 v[76:77], v[50:53], off offset:256
	s_and_saveexec_b64 s[10:11], s[4:5]
	s_cbranch_execz .LBB0_1026
	s_waitcnt lgkmcnt(0)
	v_add_f32_e32 v48, v48, v49
	ds_write_b32 v112, v48 offset:2048
; __device__ __forceinline__ unsigned cvt_pk_bf16(float lo, float hi) { cvf32x2_t v = {lo, hi}; cvbf16x2_t b = __builtin_convertvector(v, cvbf16x2_t); return __builtin_bit_cast(unsigned, b); }
; __device__ __forceinline__ float bfl(unsigned w) { return __uint_as_float(w << 16); }
; __device__ __forceinline__ float bfh(unsigned w) { return __uint_as_float(w & 0xffff0000u); }
;     __device__ __forceinline__ void fused(f32x4 (&acc)[2][2][4][2], const Unit& u, int wr, int wc, int fr, int fq, PG8_LAS unsigned char* lds, int wid, int lane) const {
;     ...
;             for (int m = 0; m < 4; ++m) { const int row = row0 + ai * HALF + m * 16; const size_t off = (size_t)row * 1024 + col0; float ss = 0.f;
; #pragma unroll
;                 for (int bj = 0; bj < 2; ++bj) { const size_t o = off + bj * HALF; f32x4 x0, x1;
;                     if (xin32) { x0 = *(const f32x4*)(xin32 + o); x1 = *(const f32x4*)(xin32 + o + 4); }
;                     else { const u32x4 w = *(const u32x4*)(xb + o); x0 = (f32x4){bfl(w.x), bfh(w.x), bfl(w.y), bfh(w.y)}; x1 = (f32x4){bfl(w.z), bfh(w.z), bfl(w.w), bfh(w.w)}; }
;                     const f32x4 v0 = x0 + acc[ai][bj][m][0] * scale, v1 = x1 + acc[ai][bj][m][1] * scale;
;                     ss += ((v0[0] * v0[0] + v0[1] * v0[1]) + (v0[2] * v0[2] + v0[3] * v0[3])) + ((v1[0] * v1[0] + v1[1] * v1[1]) + (v1[2] * v1[2] + v1[3] * v1[3]));
;                     u32x4 w; w.x = cvt_pk_bf16(v0[0], v0[1]); w.y = cvt_pk_bf16(v0[2], v0[3]); w.z = cvt_pk_bf16(v1[0], v1[1]); w.w = cvt_pk_bf16(v1[2], v1[3]); st_wt16(xb + o, w); }
;                 ss += __shfl_xor(ss, 16); ss += __shfl_xor(ss, 32);
;                 if (fq == 0) P[(ai * HALF + wr * 64 + m * 16 + fr) * 4 + wc] = ss; }
.LBB0_1026:
	s_or_b64 exec, exec, s[10:11]
	v_add_co_u32_e32 v56, vcc, 0x48000, v64
	s_mov_b64 s[10:11], 0x48000
	s_nop 0
	v_addc_co_u32_e32 v57, vcc, 0, v65, vcc
	v_lshl_add_u64 v[58:59], v[64:65], 0, s[10:11]
	s_waitcnt lgkmcnt(0)
	v_lshlrev_b32_e32 v60, 16, v196
	v_and_b32_e32 v61, 0xffff0000, v196
	v_lshlrev_b32_e32 v48, 16, v197
	v_and_b32_e32 v49, 0xffff0000, v197
	v_lshlrev_b32_e32 v62, 16, v198
	v_and_b32_e32 v63, 0xffff0000, v198
	v_lshlrev_b32_e32 v50, 16, v199
	v_and_b32_e32 v51, 0xffff0000, v199
	v_lshlrev_b32_e32 v64, 16, v200
	v_and_b32_e32 v65, 0xffff0000, v200
	v_lshlrev_b32_e32 v52, 16, v201
	v_and_b32_e32 v53, 0xffff0000, v201
	v_lshlrev_b32_e32 v66, 16, v202
	v_and_b32_e32 v67, 0xffff0000, v202
	v_lshlrev_b32_e32 v54, 16, v203
	v_and_b32_e32 v55, 0xffff0000, v203
	v_pk_add_f32 v[46:47], v[46:47], v[48:49]
	v_pk_add_f32 v[44:45], v[44:45], v[60:61]
	v_pk_add_f32 v[42:43], v[42:43], v[50:51]
	v_pk_add_f32 v[40:41], v[40:41], v[62:63]
	v_pk_add_f32 v[38:39], v[38:39], v[52:53]
	v_pk_add_f32 v[36:37], v[36:37], v[64:65]
	v_pk_add_f32 v[48:49], v[34:35], v[54:55]
	v_pk_add_f32 v[50:51], v[32:33], v[66:67]
	v_mul_f32_e32 v34, v45, v45
	v_mul_f32_e32 v35, v47, v47
	v_mul_f32_e32 v52, v41, v41
	v_mul_f32_e32 v53, v43, v43
	v_cvt_pk_bf16_f32 v32, v44, v45
	v_cvt_pk_bf16_f32 v33, v46, v47
	v_mul_f32_e32 v45, v37, v37
	v_mul_f32_e32 v47, v39, v39
	v_mul_f32_e32 v54, v51, v51
	v_mul_f32_e32 v55, v49, v49
	v_fmac_f32_e32 v34, v44, v44
	v_fmac_f32_e32 v35, v46, v46
	v_fmac_f32_e32 v52, v40, v40
	v_fmac_f32_e32 v53, v42, v42
	v_fmac_f32_e32 v45, v36, v36
	v_fmac_f32_e32 v47, v38, v38
	v_fmac_f32_e32 v54, v50, v50
	v_fmac_f32_e32 v55, v48, v48
	v_add_f32_e32 v34, v34, v35
	v_add_f32_e32 v35, v52, v53
	v_add_f32_e32 v44, v45, v47
	v_add_f32_e32 v45, v54, v55
	v_add_f32_e32 v34, v34, v35
	v_add_f32_e32 v35, v44, v45
	v_add_f32_e32 v44, v34, v35
	ds_bpermute_b32 v45, v133, v44
	v_cvt_pk_bf16_f32 v34, v40, v41
	v_cvt_pk_bf16_f32 v35, v42, v43
	global_store_dwordx4 v[56:57], v[32:35], off
	s_waitcnt lgkmcnt(0)
	s_nop 0
	v_add_f32_e32 v32, v44, v45
	ds_bpermute_b32 v33, v132, v32
	v_cvt_pk_bf16_f32 v34, v36, v37
	v_cvt_pk_bf16_f32 v35, v38, v39
	v_cvt_pk_bf16_f32 v36, v50, v51
	v_cvt_pk_bf16_f32 v37, v48, v49
	global_store_dwordx4 v[58:59], v[34:37], off offset:256
	s_and_saveexec_b64 s[10:11], s[4:5]
	s_cbranch_execz .LBB0_1028
	s_waitcnt lgkmcnt(0)
	v_add_f32_e32 v32, v32, v33
	ds_write_b32 v112, v32 offset:2304
; __device__ __forceinline__ unsigned cvt_pk_bf16(float lo, float hi) { cvf32x2_t v = {lo, hi}; cvbf16x2_t b = __builtin_convertvector(v, cvbf16x2_t); return __builtin_bit_cast(unsigned, b); }
; __device__ __forceinline__ float bfl(unsigned w) { return __uint_as_float(w << 16); }
; __device__ __forceinline__ float bfh(unsigned w) { return __uint_as_float(w & 0xffff0000u); }
;     __device__ __forceinline__ void fused(f32x4 (&acc)[2][2][4][2], const Unit& u, int wr, int wc, int fr, int fq, PG8_LAS unsigned char* lds, int wid, int lane) const {
;     ...
;             for (int m = 0; m < 4; ++m) { const int row = row0 + ai * HALF + m * 16; const size_t off = (size_t)row * 1024 + col0; float ss = 0.f;
; #pragma unroll
;                 for (int bj = 0; bj < 2; ++bj) { const size_t o = off + bj * HALF; f32x4 x0, x1;
;                     if (xin32) { x0 = *(const f32x4*)(xin32 + o); x1 = *(const f32x4*)(xin32 + o + 4); }
;                     else { const u32x4 w = *(const u32x4*)(xb + o); x0 = (f32x4){bfl(w.x), bfh(w.x), bfl(w.y), bfh(w.y)}; x1 = (f32x4){bfl(w.z), bfh(w.z), bfl(w.w), bfh(w.w)}; }
;                     const f32x4 v0 = x0 + acc[ai][bj][m][0] * scale, v1 = x1 + acc[ai][bj][m][1] * scale;
;                     ss += ((v0[0] * v0[0] + v0[1] * v0[1]) + (v0[2] * v0[2] + v0[3] * v0[3])) + ((v1[0] * v1[0] + v1[1] * v1[1]) + (v1[2] * v1[2] + v1[3] * v1[3]));
;                     u32x4 w; w.x = cvt_pk_bf16(v0[0], v0[1]); w.y = cvt_pk_bf16(v0[2], v0[3]); w.z = cvt_pk_bf16(v1[0], v1[1]); w.w = cvt_pk_bf16(v1[2], v1[3]); st_wt16(xb + o, w); }
;                 ss += __shfl_xor(ss, 16); ss += __shfl_xor(ss, 32);
;                 if (fq == 0) P[(ai * HALF + wr * 64 + m * 16 + fr) * 4 + wc] = ss; }
.LBB0_1028:
	s_or_b64 exec, exec, s[10:11]
	s_waitcnt lgkmcnt(0)
	v_lshlrev_b64 v[32:33], 10, v[128:129]
	v_lshl_add_u64 v[32:33], v[32:33], 0, v[130:131]
	v_lshl_add_u64 v[32:33], v[32:33], 1, s[54:55]
	v_add_co_u32_e32 v42, vcc, 0x50000, v32
	s_mov_b64 s[10:11], 0x50000
	s_nop 0
	v_addc_co_u32_e32 v43, vcc, 0, v33, vcc
	v_lshl_add_u64 v[44:45], v[32:33], 0, s[10:11]
	v_lshlrev_b32_e32 v46, 16, v204
	v_and_b32_e32 v47, 0xffff0000, v204
	v_lshlrev_b32_e32 v34, 16, v205
	v_and_b32_e32 v35, 0xffff0000, v205
	v_lshlrev_b32_e32 v48, 16, v206
	v_and_b32_e32 v49, 0xffff0000, v206
	v_lshlrev_b32_e32 v36, 16, v207
	v_and_b32_e32 v37, 0xffff0000, v207
	v_lshlrev_b32_e32 v50, 16, v212
	v_and_b32_e32 v51, 0xffff0000, v212
	v_lshlrev_b32_e32 v38, 16, v213
	v_and_b32_e32 v39, 0xffff0000, v213
	v_lshlrev_b32_e32 v52, 16, v214
	v_and_b32_e32 v53, 0xffff0000, v214
	v_lshlrev_b32_e32 v40, 16, v215
	v_and_b32_e32 v41, 0xffff0000, v215
	v_pk_add_f32 v[30:31], v[30:31], v[34:35]
	v_pk_add_f32 v[28:29], v[28:29], v[46:47]
	v_pk_add_f32 v[26:27], v[26:27], v[36:37]
	v_pk_add_f32 v[24:25], v[24:25], v[48:49]
	v_pk_add_f32 v[22:23], v[22:23], v[38:39]
	v_pk_add_f32 v[20:21], v[20:21], v[50:51]
	v_pk_add_f32 v[34:35], v[18:19], v[40:41]
	v_pk_add_f32 v[36:37], v[16:17], v[52:53]
	v_mul_f32_e32 v18, v29, v29
	v_mul_f32_e32 v19, v31, v31
	v_mul_f32_e32 v38, v25, v25
	v_mul_f32_e32 v39, v27, v27
	v_cvt_pk_bf16_f32 v16, v28, v29
	v_cvt_pk_bf16_f32 v17, v30, v31
	v_mul_f32_e32 v29, v21, v21
	v_mul_f32_e32 v31, v23, v23
	v_mul_f32_e32 v40, v37, v37
	v_mul_f32_e32 v41, v35, v35
	v_fmac_f32_e32 v18, v28, v28
	v_fmac_f32_e32 v19, v30, v30
	v_fmac_f32_e32 v38, v24, v24
	v_fmac_f32_e32 v39, v26, v26
	v_fmac_f32_e32 v29, v20, v20
	v_fmac_f32_e32 v31, v22, v22
	v_fmac_f32_e32 v40, v36, v36
	v_fmac_f32_e32 v41, v34, v34
	v_add_f32_e32 v18, v18, v19
	v_add_f32_e32 v19, v38, v39
	v_add_f32_e32 v28, v29, v31
	v_add_f32_e32 v29, v40, v41
	v_add_f32_e32 v18, v18, v19
	v_add_f32_e32 v19, v28, v29
	v_add_f32_e32 v28, v18, v19
	ds_bpermute_b32 v29, v133, v28
	v_cvt_pk_bf16_f32 v18, v24, v25
	v_cvt_pk_bf16_f32 v19, v26, v27
	global_store_dwordx4 v[42:43], v[16:19], off
	s_waitcnt lgkmcnt(0)
	s_nop 0
	v_add_f32_e32 v16, v28, v29
	ds_bpermute_b32 v17, v132, v16
	v_cvt_pk_bf16_f32 v18, v20, v21
	v_cvt_pk_bf16_f32 v19, v22, v23
	v_cvt_pk_bf16_f32 v20, v36, v37
	v_cvt_pk_bf16_f32 v21, v34, v35
	global_store_dwordx4 v[44:45], v[18:21], off offset:256
	s_and_saveexec_b64 s[10:11], s[4:5]
	s_cbranch_execz .LBB0_1030
	s_waitcnt lgkmcnt(0)
	v_add_f32_e32 v16, v16, v17
	ds_write_b32 v112, v16 offset:2560
.LBB0_1030:
	s_or_b64 exec, exec, s[10:11]
	v_add_co_u32_e32 v24, vcc, 0x58000, v32
	s_mov_b64 s[10:11], 0x58000
	s_nop 0
	v_addc_co_u32_e32 v25, vcc, 0, v33, vcc
	v_lshl_add_u64 v[26:27], v[32:33], 0, s[10:11]
	s_waitcnt lgkmcnt(0)
	v_lshlrev_b32_e32 v28, 16, v216
	v_and_b32_e32 v29, 0xffff0000, v216
	v_lshlrev_b32_e32 v16, 16, v217
	v_and_b32_e32 v17, 0xffff0000, v217
	v_lshlrev_b32_e32 v30, 16, v218
	v_and_b32_e32 v31, 0xffff0000, v218
	v_lshlrev_b32_e32 v18, 16, v219
	v_and_b32_e32 v19, 0xffff0000, v219
	v_lshlrev_b32_e32 v32, 16, v220
	v_and_b32_e32 v33, 0xffff0000, v220
	v_lshlrev_b32_e32 v20, 16, v221
	v_and_b32_e32 v21, 0xffff0000, v221
	v_lshlrev_b32_e32 v34, 16, v222
	v_and_b32_e32 v35, 0xffff0000, v222
	v_lshlrev_b32_e32 v22, 16, v223
	v_and_b32_e32 v23, 0xffff0000, v223
	v_pk_add_f32 v[14:15], v[14:15], v[16:17]
	v_pk_add_f32 v[12:13], v[12:13], v[28:29]
	v_pk_add_f32 v[10:11], v[10:11], v[18:19]
	v_pk_add_f32 v[8:9], v[8:9], v[30:31]
	v_pk_add_f32 v[6:7], v[6:7], v[20:21]
	v_pk_add_f32 v[4:5], v[4:5], v[32:33]
	v_pk_add_f32 v[16:17], v[2:3], v[22:23]
	v_pk_add_f32 v[18:19], v[0:1], v[34:35]
	v_mul_f32_e32 v2, v13, v13
	v_mul_f32_e32 v3, v15, v15
	v_mul_f32_e32 v20, v9, v9
	v_mul_f32_e32 v21, v11, v11
	v_cvt_pk_bf16_f32 v0, v12, v13
	v_cvt_pk_bf16_f32 v1, v14, v15
	v_mul_f32_e32 v13, v5, v5
	v_mul_f32_e32 v15, v7, v7
	v_mul_f32_e32 v22, v19, v19
	v_mul_f32_e32 v23, v17, v17
	v_fmac_f32_e32 v2, v12, v12
	v_fmac_f32_e32 v3, v14, v14
	v_fmac_f32_e32 v20, v8, v8
	v_fmac_f32_e32 v21, v10, v10
	v_fmac_f32_e32 v13, v4, v4
	v_fmac_f32_e32 v15, v6, v6
	v_fmac_f32_e32 v22, v18, v18
	v_fmac_f32_e32 v23, v16, v16
	v_add_f32_e32 v2, v2, v3
	v_add_f32_e32 v3, v20, v21
	v_add_f32_e32 v12, v13, v15
	v_add_f32_e32 v13, v22, v23
	v_add_f32_e32 v2, v2, v3
	v_add_f32_e32 v3, v12, v13
	v_add_f32_e32 v12, v2, v3
	ds_bpermute_b32 v13, v133, v12
	v_cvt_pk_bf16_f32 v2, v8, v9
	v_cvt_pk_bf16_f32 v3, v10, v11
	global_store_dwordx4 v[24:25], v[0:3], off
	s_waitcnt lgkmcnt(0)
	s_nop 0
	v_add_f32_e32 v0, v12, v13
	ds_bpermute_b32 v1, v132, v0
	v_cvt_pk_bf16_f32 v2, v4, v5
	v_cvt_pk_bf16_f32 v3, v6, v7
	v_cvt_pk_bf16_f32 v4, v18, v19
	v_cvt_pk_bf16_f32 v5, v16, v17
	global_store_dwordx4 v[26:27], v[2:5], off offset:256
	s_and_saveexec_b64 s[10:11], s[4:5]
	s_cbranch_execz .LBB0_1032
	s_waitcnt lgkmcnt(0)
	v_add_f32_e32 v0, v0, v1
	ds_write_b32 v112, v0 offset:2816
